# ml_post: full-wave sums via DPP row reduce + readlane combine instead of ds_bpermute butterflies
# speedup vs baseline: 1.0247x; 1.0030x over previous
.LBB0_871:
	v_lshl_add_u64 v[2:3], v[60:61], 0, v[56:57]
	v_add_co_u32_e32 v4, vcc, 0x3200000, v2
	s_mov_b32 s4, 0x358637bd
	s_nop 0
	v_addc_co_u32_e32 v5, vcc, 0, v3, vcc
	v_add_co_u32_e32 v62, vcc, 0x3201000, v2
	global_load_dwordx4 v[74:77], v[4:5], off
	s_nop 0
	v_addc_co_u32_e32 v63, vcc, 0, v3, vcc
	global_load_dwordx4 v[78:81], v[62:63], off
	v_lshl_add_u64 v[2:3], v[58:59], 0, v[56:57]
	v_add_co_u32_e32 v2, vcc, 0x13200000, v2
	v_add_u32_e32 v42, s6, v42
	s_nop 0
	v_addc_co_u32_e32 v3, vcc, 0, v3, vcc
	global_load_dwordx4 v[82:85], v[2:3], off
	global_load_dwordx4 v[102:105], v[4:5], off offset:1024
	global_load_dwordx4 v[106:109], v[62:63], off offset:1024
	global_load_dwordx4 v[110:113], v[2:3], off offset:1024
	global_load_dwordx4 v[22:25], v[4:5], off offset:2048
	global_load_dwordx4 v[18:21], v[62:63], off offset:2048
	global_load_dwordx4 v[14:17], v[2:3], off offset:2048
	global_load_dwordx4 v[10:13], v[4:5], off offset:3072
	global_load_dwordx4 v[6:9], v[62:63], off offset:3072
	s_nop 0
	global_load_dwordx4 v[2:5], v[2:3], off offset:3072
	s_nop 0
	global_load_dwordx4 v[26:29], v[44:45], off offset:16
	global_load_dwordx4 v[34:37], v[44:45], off
	global_load_dwordx4 v[30:33], v[46:47], off offset:16
	global_load_dwordx4 v[38:41], v[46:47], off
	v_lshl_add_u64 v[58:59], v[58:59], 0, s[8:9]
	v_lshl_add_u64 v[60:61], v[60:61], 0, s[10:11]
	s_waitcnt vmcnt(13)
	v_lshlrev_b32_e32 v66, 16, v84
	v_and_b32_e32 v67, 0xffff0000, v84
	v_lshlrev_b32_e32 v64, 16, v85
	v_lshlrev_b32_e32 v92, 16, v76
	v_and_b32_e32 v93, 0xffff0000, v76
	v_lshlrev_b32_e32 v88, 16, v75
	v_lshlrev_b32_e32 v68, 16, v80
	v_mul_f32_e32 v43, 0xbfb8aa3b, v68
	v_exp_f32_e32 v43, v43
	v_and_b32_e32 v69, 0xffff0000, v80
	v_lshlrev_b32_e32 v90, 16, v81
	v_lshlrev_b32_e32 v72, 16, v79
	v_add_f32_e32 v43, 1.0, v43
	v_rcp_f32_e32 v70, v43
	v_mul_f32_e32 v43, 0xbfb8aa3b, v69
	v_exp_f32_e32 v43, v43
	v_and_b32_e32 v73, 0xffff0000, v79
	v_and_b32_e32 v89, 0xffff0000, v75
	v_lshlrev_b32_e32 v94, 16, v74
	v_add_f32_e32 v43, 1.0, v43
	v_rcp_f32_e32 v71, v43
	v_mul_f32_e32 v43, 0xbfb8aa3b, v90
	v_exp_f32_e32 v43, v43
	v_and_b32_e32 v95, 0xffff0000, v74
	v_lshlrev_b32_e32 v74, 16, v78
	v_and_b32_e32 v75, 0xffff0000, v78
	v_add_f32_e32 v43, 1.0, v43
	v_rcp_f32_e32 v84, v43
	v_mul_f32_e32 v43, 0xbfb8aa3b, v72
	v_exp_f32_e32 v43, v43
	v_mul_f32_e32 v78, 0xbfb8aa3b, v74
	v_mul_f32_e32 v79, 0xbfb8aa3b, v75
	v_exp_f32_e32 v78, v78
	v_add_f32_e32 v43, 1.0, v43
	v_rcp_f32_e32 v76, v43
	v_mul_f32_e32 v43, 0xbfb8aa3b, v73
	v_exp_f32_e32 v43, v43
	v_exp_f32_e32 v79, v79
	v_lshlrev_b32_e32 v86, 16, v77
	v_and_b32_e32 v87, 0xffff0000, v77
	v_add_f32_e32 v43, 1.0, v43
	v_rcp_f32_e32 v77, v43
	v_add_f32_e32 v43, 0, v94
	v_add_f32_e32 v43, v43, v95
	v_add_f32_e32 v43, v43, v88
	v_add_f32_e32 v78, 1.0, v78
	v_add_f32_e32 v79, 1.0, v79
	v_add_f32_e32 v43, v43, v89
	v_rcp_f32_e32 v78, v78
	v_rcp_f32_e32 v79, v79
	v_add_f32_e32 v43, v43, v92
	v_add_f32_e32 v43, v43, v93
	v_add_f32_e32 v43, v43, v86
	v_add_f32_e32 v43, v43, v87
	v_and_b32_e32 v91, 0xffff0000, v81
	v_pk_mul_f32 v[80:81], v[78:79], v[74:75]
	s_nop 0
	v_and_b32_e32 v65, 0xffff0000, v85
	s_waitcnt vmcnt(11)
	v_lshlrev_b32_e32 v100, 16, v107
	v_and_b32_e32 v101, 0xffff0000, v107
	v_lshlrev_b32_e32 v126, 16, v104
	s_nop 0
	s_nop 0
	s_nop 0
	v_and_b32_e32 v127, 0xffff0000, v104
	v_lshlrev_b32_e32 v124, 16, v105
	v_and_b32_e32 v125, 0xffff0000, v105
	v_pk_mul_f32 v[68:69], v[70:71], v[68:69]
	s_nop 0
	s_nop 0
	s_nop 0
	v_lshlrev_b32_e32 v70, 16, v83
	v_and_b32_e32 v71, 0xffff0000, v83
	v_pk_mul_f32 v[72:73], v[76:77], v[72:73]
	v_lshlrev_b32_e32 v76, 16, v82
	s_nop 0
	s_nop 0
	s_nop 0
	v_and_b32_e32 v77, 0xffff0000, v82
	s_waitcnt vmcnt(10)
	v_lshlrev_b32_e32 v82, 16, v112
	v_and_b32_e32 v83, 0xffff0000, v112
	v_lshlrev_b32_e32 v112, 16, v102
	s_nop 0
	s_nop 0
	s_nop 0
	v_lshlrev_b32_e32 v78, 16, v113
	v_and_b32_e32 v79, 0xffff0000, v113
	v_and_b32_e32 v113, 0xffff0000, v102
	v_lshlrev_b32_e32 v98, 16, v111
	s_nop 0
	s_nop 0
	s_nop 0
	v_and_b32_e32 v99, 0xffff0000, v111
	v_lshlrev_b32_e32 v102, 16, v110
	s_nop 0
	s_nop 1
	v_add_f32_dpp v74, v43, v43 quad_perm:[1,0,3,2] row_mask:0xf bank_mask:0xf
	s_nop 1
	v_add_f32_dpp v74, v74, v74 quad_perm:[2,3,0,1] row_mask:0xf bank_mask:0xf
	s_nop 1
	v_add_f32_dpp v74, v74, v74 row_half_mirror row_mask:0xf bank_mask:0xf
	s_nop 1
	v_add_f32_dpp v74, v74, v74 row_mirror row_mask:0xf bank_mask:0xf
	s_nop 1
	v_readlane_b32 s60, v74, 0
	v_readlane_b32 s61, v74, 16
	v_readlane_b32 s62, v74, 32
	v_readlane_b32 s63, v74, 48
	s_nop 2
	v_mov_b32_e32 v43, s60
	v_add_f32_e32 v43, s61, v43
	v_add_f32_e32 v43, s62, v43
	v_add_f32_e32 v43, s63, v43
	v_mul_f32_e32 v74, 0x3b000000, v43
	v_mul_f32_e32 v43, 0xbfb8aa3b, v91
	v_exp_f32_e32 v43, v43
	v_pk_add_f32 v[96:97], v[94:95], v[74:75] op_sel_hi:[1,0] neg_lo:[0,1] neg_hi:[0,1]
	v_pk_add_f32 v[94:95], v[92:93], v[74:75] op_sel_hi:[1,0] neg_lo:[0,1] neg_hi:[0,1]
	v_pk_add_f32 v[88:89], v[88:89], v[74:75] op_sel_hi:[1,0] neg_lo:[0,1] neg_hi:[0,1]
	v_add_f32_e32 v43, 1.0, v43
	v_rcp_f32_e32 v85, v43
	v_pk_add_f32 v[86:87], v[86:87], v[74:75] op_sel_hi:[1,0] neg_lo:[0,1] neg_hi:[0,1]
	v_lshlrev_b32_e32 v74, 16, v109
	v_and_b32_e32 v75, 0xffff0000, v109
	v_pk_mul_f32 v[92:93], v[84:85], v[90:91]
	v_lshlrev_b32_e32 v84, 16, v108
	v_mul_f32_e32 v43, 0xbfb8aa3b, v84
	v_exp_f32_e32 v43, v43
	v_and_b32_e32 v85, 0xffff0000, v108
	v_lshlrev_b32_e32 v108, 16, v103
	v_and_b32_e32 v109, 0xffff0000, v103
	v_add_f32_e32 v43, 1.0, v43
	v_rcp_f32_e32 v90, v43
	v_mul_f32_e32 v43, 0xbfb8aa3b, v85
	v_exp_f32_e32 v43, v43
	v_and_b32_e32 v103, 0xffff0000, v110
	v_mov_b32_e32 v131, v97
	v_pk_mul_f32 v[114:115], v[94:95], v[94:95]
	v_add_f32_e32 v43, 1.0, v43
	v_rcp_f32_e32 v91, v43
	v_mul_f32_e32 v43, 0xbfb8aa3b, v74
	v_exp_f32_e32 v43, v43
	v_pk_mul_f32 v[122:123], v[86:87], v[86:87]
	v_pk_mul_f32 v[90:91], v[90:91], v[84:85]
	v_add_f32_e32 v43, 1.0, v43
	v_rcp_f32_e32 v84, v43
	v_mul_f32_e32 v43, 0xbfb8aa3b, v100
	v_exp_f32_e32 v43, v43
	s_nop 0
	v_add_f32_e32 v43, 1.0, v43
	v_rcp_f32_e32 v104, v43
	v_mul_f32_e32 v43, 0xbfb8aa3b, v101
	v_exp_f32_e32 v43, v43
	s_nop 0
	v_add_f32_e32 v43, 1.0, v43
	v_rcp_f32_e32 v105, v43
	v_add_f32_e32 v43, 0, v112
	v_add_f32_e32 v43, v43, v113
	v_add_f32_e32 v43, v43, v108
	v_pk_mul_f32 v[100:101], v[104:105], v[100:101]
	v_lshlrev_b32_e32 v104, 16, v106
	v_mul_f32_e32 v85, 0xbfb8aa3b, v104
	v_exp_f32_e32 v85, v85
	v_and_b32_e32 v105, 0xffff0000, v106
	v_add_f32_e32 v43, v43, v109
	v_add_f32_e32 v43, v43, v126
	v_add_f32_e32 v85, 1.0, v85
	v_rcp_f32_e32 v106, v85
	v_mul_f32_e32 v85, 0xbfb8aa3b, v105
	v_exp_f32_e32 v85, v85
	v_add_f32_e32 v43, v43, v127
	v_add_f32_e32 v43, v43, v124
	v_add_f32_e32 v43, v43, v125
	v_add_f32_e32 v85, 1.0, v85
	v_rcp_f32_e32 v107, v85
	s_nop 0
	v_pk_mul_f32 v[104:105], v[106:107], v[104:105]
	s_nop 0
	s_nop 0
	s_nop 0
	s_nop 0
	s_nop 0
	s_nop 0
	s_nop 0
	s_nop 0
	s_nop 0
	s_nop 0
	s_nop 0
	s_nop 0
	s_nop 0
	s_nop 0
	s_nop 0
	s_nop 0
	s_nop 1
	v_add_f32_dpp v85, v43, v43 quad_perm:[1,0,3,2] row_mask:0xf bank_mask:0xf
	s_nop 1
	v_add_f32_dpp v85, v85, v85 quad_perm:[2,3,0,1] row_mask:0xf bank_mask:0xf
	s_nop 1
	v_add_f32_dpp v85, v85, v85 row_half_mirror row_mask:0xf bank_mask:0xf
	s_nop 1
	v_add_f32_dpp v85, v85, v85 row_mirror row_mask:0xf bank_mask:0xf
	s_nop 1
	v_readlane_b32 s60, v85, 0
	v_readlane_b32 s61, v85, 16
	v_readlane_b32 s62, v85, 32
	v_readlane_b32 s63, v85, 48
	s_nop 2
	v_mov_b32_e32 v43, s60
	v_add_f32_e32 v43, s61, v43
	v_add_f32_e32 v43, s62, v43
	v_add_f32_e32 v43, s63, v43
	v_mul_f32_e32 v128, 0x3b000000, v43
	v_pk_add_f32 v[110:111], v[112:113], v[128:129] op_sel_hi:[1,0] neg_lo:[0,1] neg_hi:[0,1]
	v_pk_add_f32 v[106:107], v[108:109], v[128:129] op_sel_hi:[1,0] neg_lo:[0,1] neg_hi:[0,1]
	v_mov_b32_e32 v130, v111
	v_mov_b32_e32 v112, v110
	v_mov_b32_e32 v113, v96
	v_pk_mul_f32 v[130:131], v[130:131], v[130:131]
	v_pk_add_f32 v[108:109], v[126:127], v[128:129] op_sel_hi:[1,0] neg_lo:[0,1] neg_hi:[0,1]
	v_pk_fma_f32 v[112:113], v[112:113], v[112:113], v[130:131]
	v_mov_b32_e32 v130, v106
	v_mov_b32_e32 v131, v88
	v_pk_mul_f32 v[126:127], v[108:109], v[108:109]
	v_pk_fma_f32 v[112:113], v[130:131], v[130:131], v[112:113]
	v_mov_b32_e32 v130, v107
	v_mov_b32_e32 v131, v89
	v_pk_fma_f32 v[112:113], v[130:131], v[130:131], v[112:113]
	v_mov_b32_e32 v130, v126
	v_mov_b32_e32 v131, v114
	v_pk_add_f32 v[130:131], v[130:131], v[112:113]
	v_pk_add_f32 v[112:113], v[124:125], v[128:129] op_sel_hi:[1,0] neg_lo:[0,1] neg_hi:[0,1]
	v_mov_b32_e32 v114, v127
	v_pk_mul_f32 v[124:125], v[112:113], v[112:113]
	v_pk_add_f32 v[114:115], v[114:115], v[130:131]
	v_mov_b32_e32 v126, v124
	v_mov_b32_e32 v127, v122
	v_pk_add_f32 v[114:115], v[126:127], v[114:115]
	v_mov_b32_e32 v122, v125
	v_pk_add_f32 v[114:115], v[122:123], v[114:115]
	s_nop 0
	s_nop 0
	s_nop 0
	s_nop 0
	s_nop 0
	s_nop 0
	s_nop 0
	s_nop 0
	s_nop 0
	s_nop 0
	s_nop 0
	s_nop 0
	s_nop 0
	s_nop 0
	s_nop 0
	s_nop 0
	s_nop 0
	s_nop 0
	s_nop 0
	s_nop 0
	s_nop 0
	s_nop 0
	s_nop 0
	s_nop 1
	v_add_f32_dpp v122, v114, v114 quad_perm:[1,0,3,2] row_mask:0xf bank_mask:0xf
	s_nop 1
	v_add_f32_dpp v122, v122, v122 quad_perm:[2,3,0,1] row_mask:0xf bank_mask:0xf
	s_nop 1
	v_add_f32_dpp v122, v122, v122 row_half_mirror row_mask:0xf bank_mask:0xf
	s_nop 1
	v_add_f32_dpp v122, v122, v122 row_mirror row_mask:0xf bank_mask:0xf
	v_add_f32_dpp v123, v115, v115 quad_perm:[1,0,3,2] row_mask:0xf bank_mask:0xf
	s_nop 1
	v_add_f32_dpp v123, v123, v123 quad_perm:[2,3,0,1] row_mask:0xf bank_mask:0xf
	s_nop 1
	v_add_f32_dpp v123, v123, v123 row_half_mirror row_mask:0xf bank_mask:0xf
	s_nop 1
	v_add_f32_dpp v123, v123, v123 row_mirror row_mask:0xf bank_mask:0xf
	s_nop 1
	v_readlane_b32 s60, v122, 0
	v_readlane_b32 s61, v122, 16
	v_readlane_b32 s62, v122, 32
	v_readlane_b32 s63, v122, 48
	s_nop 2
	v_mov_b32_e32 v122, s60
	v_add_f32_e32 v122, s61, v122
	v_add_f32_e32 v122, s62, v122
	v_add_f32_e32 v122, s63, v122
	v_readlane_b32 s60, v123, 0
	v_readlane_b32 s61, v123, 16
	v_readlane_b32 s62, v123, 32
	v_readlane_b32 s63, v123, 48
	s_nop 2
	v_mov_b32_e32 v123, s60
	v_add_f32_e32 v123, s61, v123
	v_add_f32_e32 v123, s62, v123
	v_add_f32_e32 v123, s63, v123
	v_mov_b64_e32 v[114:115], s[4:5]
	v_pk_fma_f32 v[122:123], v[122:123], s[16:17], v[114:115] op_sel_hi:[1,0,0]
	s_nop 0
	v_mul_f32_e32 v43, 0x4b800000, v123
	v_cmp_gt_f32_e64 s[4:5], s71, v123
	v_cmp_gt_f32_e32 vcc, s71, v122
	s_nop 0
	v_cndmask_b32_e64 v43, v123, v43, s[4:5]
	v_rsq_f32_e32 v43, v43
	s_nop 0
	v_mul_f32_e32 v85, 0x45800000, v43
	v_cndmask_b32_e64 v124, v43, v85, s[4:5]
	v_pk_mul_f32 v[96:97], v[96:97], v[124:125] op_sel_hi:[1,0]
	v_mul_f32_e32 v43, 0x4b800000, v122
	s_waitcnt vmcnt(2)
	v_pk_mul_f32 v[34:35], v[34:35], v[96:97]
	v_cndmask_b32_e32 v43, v122, v43, vcc
	s_waitcnt vmcnt(0)
	v_pk_fma_f32 v[34:35], v[38:39], v[76:77], v[34:35]
	v_pk_mul_f32 v[38:39], v[94:95], v[124:125] op_sel_hi:[1,0]
	v_pk_mul_f32 v[34:35], v[80:81], v[34:35]
	v_pk_mul_f32 v[26:27], v[26:27], v[38:39]
	v_rsq_f32_e32 v43, v43
	v_pk_fma_f32 v[26:27], v[30:31], v[66:67], v[26:27]
	v_lshlrev_b32_e32 v76, 16, v15
	v_pk_mul_f32 v[30:31], v[68:69], v[26:27]
	v_pk_mul_f32 v[26:27], v[88:89], v[124:125] op_sel_hi:[1,0]
	v_and_b32_e32 v77, 0xffff0000, v15
	v_pk_mul_f32 v[26:27], v[36:37], v[26:27]
	v_lshlrev_b32_e32 v68, 16, v17
	v_pk_fma_f32 v[26:27], v[40:41], v[70:71], v[26:27]
	v_lshlrev_b32_e32 v70, 16, v24
	v_pk_mul_f32 v[36:37], v[72:73], v[26:27]
	v_pk_mul_f32 v[26:27], v[86:87], v[124:125] op_sel_hi:[1,0]
	v_and_b32_e32 v71, 0xffff0000, v24
	v_pk_mul_f32 v[26:27], v[28:29], v[26:27]
	v_cvt_pk_bf16_f32 v28, v30, v31
	v_pk_fma_f32 v[26:27], v[32:33], v[64:65], v[26:27]
	v_mul_f32_e32 v64, 0x45800000, v43
	v_pk_mul_f32 v[32:33], v[92:93], v[26:27]
	v_cvt_pk_bf16_f32 v26, v34, v35
	v_cvt_pk_bf16_f32 v27, v36, v37
	v_cvt_pk_bf16_f32 v29, v32, v33
	global_store_dwordx4 v[62:63], v[26:29], off
	global_load_dwordx4 v[26:29], v[44:45], off offset:2064
	s_nop 0
	global_load_dwordx4 v[30:33], v[44:45], off offset:2048
	global_load_dwordx4 v[34:37], v[46:47], off offset:2064
	global_load_dwordx4 v[38:41], v[46:47], off offset:2048
	v_cndmask_b32_e32 v64, v43, v64, vcc
	v_pk_mul_f32 v[66:67], v[110:111], v[64:65] op_sel_hi:[1,0]
	v_lshlrev_b32_e32 v24, 16, v20
	v_and_b32_e32 v69, 0xffff0000, v17
	v_lshlrev_b32_e32 v72, 16, v23
	v_and_b32_e32 v73, 0xffff0000, v23
	v_and_b32_e32 v23, 0xffff0000, v18
	v_lshlrev_b32_e32 v86, 16, v12
	v_and_b32_e32 v87, 0xffff0000, v12
	v_lshlrev_b32_e32 v12, 16, v8
	v_lshlrev_b32_e32 v88, 16, v4
	v_and_b32_e32 v89, 0xffff0000, v4
	v_mul_f32_e32 v4, 0xbfb8aa3b, v12
	v_exp_f32_e32 v4, v4
	v_lshlrev_b32_e32 v94, 16, v3
	v_and_b32_e32 v95, 0xffff0000, v3
	v_add_f32_e32 v4, 1.0, v4
	v_rcp_f32_e32 v4, v4
	s_waitcnt vmcnt(2)
	v_pk_mul_f32 v[30:31], v[30:31], v[66:67]
	v_lshlrev_b32_e32 v66, 16, v21
	s_waitcnt vmcnt(0)
	v_pk_fma_f32 v[30:31], v[38:39], v[102:103], v[30:31]
	v_pk_mul_f32 v[38:39], v[108:109], v[64:65] op_sel_hi:[1,0]
	v_and_b32_e32 v67, 0xffff0000, v21
	v_pk_mul_f32 v[26:27], v[26:27], v[38:39]
	v_and_b32_e32 v21, 0xffff0000, v16
	v_pk_fma_f32 v[26:27], v[34:35], v[82:83], v[26:27]
	v_lshlrev_b32_e32 v82, 16, v9
	v_pk_mul_f32 v[34:35], v[90:91], v[26:27]
	v_pk_mul_f32 v[26:27], v[106:107], v[64:65] op_sel_hi:[1,0]
	v_and_b32_e32 v83, 0xffff0000, v9
	v_pk_mul_f32 v[26:27], v[32:33], v[26:27]
	v_and_b32_e32 v9, 0xffff0000, v7
	v_pk_fma_f32 v[26:27], v[40:41], v[98:99], v[26:27]
	v_lshlrev_b32_e32 v98, 16, v2
	v_pk_mul_f32 v[32:33], v[100:101], v[26:27]
	v_pk_mul_f32 v[26:27], v[112:113], v[64:65] op_sel_hi:[1,0]
	v_lshlrev_b32_e32 v64, 16, v25
	v_pk_mul_f32 v[26:27], v[28:29], v[26:27]
	v_mul_f32_e32 v28, 0xbfb8aa3b, v75
	v_exp_f32_e32 v28, v28
	v_pk_fma_f32 v[26:27], v[36:37], v[78:79], v[26:27]
	v_and_b32_e32 v65, 0xffff0000, v25
	v_and_b32_e32 v25, 0xffff0000, v20
	v_add_f32_e32 v28, 1.0, v28
	v_rcp_f32_e32 v85, v28
	v_lshlrev_b32_e32 v20, 16, v16
	v_mul_f32_e32 v16, 0xbfb8aa3b, v24
	v_mul_f32_e32 v17, 0xbfb8aa3b, v25
	v_pk_mul_f32 v[28:29], v[84:85], v[74:75]
	v_lshlrev_b32_e32 v74, 16, v19
	v_mul_f32_e32 v15, 0xbfb8aa3b, v74
	v_exp_f32_e32 v15, v15
	v_and_b32_e32 v75, 0xffff0000, v19
	v_exp_f32_e32 v16, v16
	v_exp_f32_e32 v17, v17
	v_add_f32_e32 v15, 1.0, v15
	v_rcp_f32_e32 v78, v15
	v_mul_f32_e32 v15, 0xbfb8aa3b, v75
	v_exp_f32_e32 v15, v15
	v_add_f32_e32 v16, 1.0, v16
	v_add_f32_e32 v17, 1.0, v17
	v_rcp_f32_e32 v16, v16
	v_add_f32_e32 v15, 1.0, v15
	v_rcp_f32_e32 v79, v15
	v_rcp_f32_e32 v17, v17
	v_and_b32_e32 v19, 0xffff0000, v14
	v_mul_f32_e32 v15, 0xbfb8aa3b, v23
	v_pk_mul_f32 v[74:75], v[78:79], v[74:75]
	v_lshlrev_b32_e32 v78, 16, v22
	v_and_b32_e32 v79, 0xffff0000, v22
	v_lshlrev_b32_e32 v22, 16, v18
	v_lshlrev_b32_e32 v18, 16, v14
	v_add_f32_e32 v14, 0, v78
	v_pk_mul_f32 v[16:17], v[16:17], v[24:25]
	v_add_f32_e32 v25, v14, v79
	v_mul_f32_e32 v14, 0xbfb8aa3b, v22
	v_exp_f32_e32 v14, v14
	v_exp_f32_e32 v15, v15
	v_mul_f32_e32 v24, 0xbfb8aa3b, v66
	v_exp_f32_e32 v24, v24
	v_add_f32_e32 v14, 1.0, v14
	v_add_f32_e32 v15, 1.0, v15
	v_rcp_f32_e32 v14, v14
	v_rcp_f32_e32 v15, v15
	v_add_f32_e32 v24, 1.0, v24
	v_rcp_f32_e32 v24, v24
	v_lshlrev_b32_e32 v84, 16, v5
	v_pk_mul_f32 v[14:15], v[14:15], v[22:23]
	v_add_f32_e32 v22, v25, v72
	v_mul_f32_e32 v25, 0xbfb8aa3b, v67
	v_exp_f32_e32 v25, v25
	v_and_b32_e32 v85, 0xffff0000, v5
	v_and_b32_e32 v99, 0xffff0000, v2
	v_add_f32_e32 v22, v22, v73
	v_add_f32_e32 v25, 1.0, v25
	v_rcp_f32_e32 v25, v25
	v_add_f32_e32 v22, v22, v70
	v_add_f32_e32 v22, v22, v71
	v_add_f32_e32 v22, v22, v64
	v_pk_mul_f32 v[24:25], v[24:25], v[66:67]
	v_lshlrev_b32_e32 v66, 16, v13
	v_and_b32_e32 v67, 0xffff0000, v13
	v_and_b32_e32 v13, 0xffff0000, v8
	v_mul_f32_e32 v5, 0xbfb8aa3b, v13
	v_exp_f32_e32 v5, v5
	v_lshlrev_b32_e32 v8, 16, v7
	v_mul_f32_e32 v3, 0xbfb8aa3b, v8
	v_exp_f32_e32 v3, v3
	v_add_f32_e32 v5, 1.0, v5
	v_rcp_f32_e32 v5, v5
	v_add_f32_e32 v22, v22, v65
	v_add_f32_e32 v3, 1.0, v3
	s_nop 0
	v_pk_mul_f32 v[90:91], v[4:5], v[12:13]
	v_rcp_f32_e32 v12, v3
	v_mul_f32_e32 v3, 0xbfb8aa3b, v9
	v_exp_f32_e32 v3, v3
	v_mul_f32_e32 v4, 0xbfb8aa3b, v82
	v_exp_f32_e32 v4, v4
	v_and_b32_e32 v5, 0xffff0000, v11
	v_add_f32_e32 v3, 1.0, v3
	v_rcp_f32_e32 v13, v3
	v_add_f32_e32 v4, 1.0, v4
	v_rcp_f32_e32 v92, v4
	v_lshlrev_b32_e32 v4, 16, v11
	v_pk_mul_f32 v[96:97], v[12:13], v[8:9]
	v_lshlrev_b32_e32 v8, 16, v10
	v_and_b32_e32 v9, 0xffff0000, v10
	v_lshlrev_b32_e32 v10, 16, v6
	v_and_b32_e32 v11, 0xffff0000, v6
	v_add_f32_e32 v2, 0, v8
	v_add_f32_e32 v6, v2, v9
	v_mul_f32_e32 v2, 0xbfb8aa3b, v10
	v_mul_f32_e32 v3, 0xbfb8aa3b, v11
	v_exp_f32_e32 v2, v2
	v_exp_f32_e32 v3, v3
	s_nop 0
	s_nop 0
	s_nop 0
	v_add_f32_e32 v2, 1.0, v2
	v_add_f32_e32 v3, 1.0, v3
	v_rcp_f32_e32 v2, v2
	v_rcp_f32_e32 v3, v3
	v_pk_mul_f32 v[30:31], v[104:105], v[30:31]
	v_pk_mul_f32 v[36:37], v[28:29], v[26:27]
	s_nop 0
	s_nop 0
	v_pk_mul_f32 v[100:101], v[2:3], v[10:11]
	v_add_f32_e32 v2, v6, v4
	v_add_f32_e32 v2, v2, v5
	v_add_f32_e32 v2, v2, v86
	v_add_f32_e32 v2, v2, v87
	v_add_f32_e32 v2, v2, v66
	v_add_f32_e32 v2, v2, v67
	s_nop 0
	v_cvt_pk_bf16_f32 v26, v30, v31
	v_cvt_pk_bf16_f32 v27, v32, v33
	v_cvt_pk_bf16_f32 v28, v34, v35
	v_cvt_pk_bf16_f32 v29, v36, v37
	s_nop 0
	s_nop 0
	s_nop 0
	s_nop 0
	global_store_dwordx4 v[62:63], v[26:29], off offset:1024
	global_load_dwordx4 v[26:29], v[48:49], off offset:16
	s_nop 0
	global_load_dwordx4 v[30:33], v[48:49], off
	global_load_dwordx4 v[34:37], v[50:51], off offset:16
	global_load_dwordx4 v[38:41], v[50:51], off
	s_nop 0
	s_nop 0
	s_nop 0
	s_nop 0
	s_nop 0
	s_nop 0
	s_nop 0
	s_nop 0
	s_nop 0
	s_nop 0
	s_nop 0
	s_nop 0
	s_nop 0
	s_nop 0
	s_nop 0
	s_nop 0
	s_nop 0
	s_nop 0
	s_nop 0
	s_nop 0
	s_nop 0
	s_nop 0
	s_nop 1
	v_add_f32_dpp v23, v22, v22 quad_perm:[1,0,3,2] row_mask:0xf bank_mask:0xf
	s_nop 1
	v_add_f32_dpp v23, v23, v23 quad_perm:[2,3,0,1] row_mask:0xf bank_mask:0xf
	s_nop 1
	v_add_f32_dpp v23, v23, v23 row_half_mirror row_mask:0xf bank_mask:0xf
	s_nop 1
	v_add_f32_dpp v23, v23, v23 row_mirror row_mask:0xf bank_mask:0xf
	s_nop 1
	v_readlane_b32 s60, v23, 0
	v_readlane_b32 s61, v23, 16
	v_readlane_b32 s62, v23, 32
	v_readlane_b32 s63, v23, 48
	s_nop 2
	v_mov_b32_e32 v22, s60
	v_add_f32_e32 v22, s61, v22
	v_add_f32_e32 v22, s62, v22
	v_add_f32_e32 v22, s63, v22
	v_mul_f32_e32 v22, 0x3b000000, v22
	v_pk_add_f32 v[78:79], v[78:79], v[22:23] op_sel_hi:[1,0] neg_lo:[0,1] neg_hi:[0,1]
	v_pk_add_f32 v[72:73], v[72:73], v[22:23] op_sel_hi:[1,0] neg_lo:[0,1] neg_hi:[0,1]
	s_nop 0
	s_nop 1
	v_add_f32_dpp v3, v2, v2 quad_perm:[1,0,3,2] row_mask:0xf bank_mask:0xf
	s_nop 1
	v_add_f32_dpp v3, v3, v3 quad_perm:[2,3,0,1] row_mask:0xf bank_mask:0xf
	s_nop 1
	v_add_f32_dpp v3, v3, v3 row_half_mirror row_mask:0xf bank_mask:0xf
	s_nop 1
	v_add_f32_dpp v3, v3, v3 row_mirror row_mask:0xf bank_mask:0xf
	s_nop 1
	v_readlane_b32 s60, v3, 0
	v_readlane_b32 s61, v3, 16
	v_readlane_b32 s62, v3, 32
	v_readlane_b32 s63, v3, 48
	s_nop 2
	v_mov_b32_e32 v2, s60
	v_add_f32_e32 v2, s61, v2
	v_add_f32_e32 v2, s62, v2
	v_add_f32_e32 v2, s63, v2
	v_mul_f32_e32 v2, 0x3b000000, v2
	v_pk_add_f32 v[102:103], v[8:9], v[2:3] op_sel_hi:[1,0] neg_lo:[0,1] neg_hi:[0,1]
	v_mov_b32_e32 v9, v79
	v_mov_b32_e32 v8, v103
	v_pk_add_f32 v[104:105], v[4:5], v[2:3] op_sel_hi:[1,0] neg_lo:[0,1] neg_hi:[0,1]
	v_mov_b32_e32 v6, v102
	v_mov_b32_e32 v7, v78
	v_pk_mul_f32 v[8:9], v[8:9], v[8:9]
	v_pk_add_f32 v[70:71], v[70:71], v[22:23] op_sel_hi:[1,0] neg_lo:[0,1] neg_hi:[0,1]
	v_pk_add_f32 v[86:87], v[86:87], v[2:3] op_sel_hi:[1,0] neg_lo:[0,1] neg_hi:[0,1]
	v_pk_fma_f32 v[6:7], v[6:7], v[6:7], v[8:9]
	v_mov_b32_e32 v8, v104
	v_mov_b32_e32 v9, v72
	v_pk_mul_f32 v[80:81], v[70:71], v[70:71]
	v_pk_mul_f32 v[4:5], v[86:87], v[86:87]
	v_pk_fma_f32 v[6:7], v[8:9], v[8:9], v[6:7]
	v_mov_b32_e32 v8, v105
	v_mov_b32_e32 v9, v73
	v_pk_add_f32 v[22:23], v[64:65], v[22:23] op_sel_hi:[1,0] neg_lo:[0,1] neg_hi:[0,1]
	v_pk_fma_f32 v[6:7], v[8:9], v[8:9], v[6:7]
	v_mov_b32_e32 v8, v4
	v_mov_b32_e32 v9, v80
	v_pk_add_f32 v[66:67], v[66:67], v[2:3] op_sel_hi:[1,0] neg_lo:[0,1] neg_hi:[0,1]
	v_pk_mul_f32 v[64:65], v[22:23], v[22:23]
	v_pk_add_f32 v[6:7], v[8:9], v[6:7]
	v_pk_mul_f32 v[2:3], v[66:67], v[66:67]
	v_mov_b32_e32 v80, v5
	v_pk_add_f32 v[4:5], v[80:81], v[6:7]
	v_mov_b32_e32 v6, v2
	v_mov_b32_e32 v7, v64
	v_pk_add_f32 v[4:5], v[6:7], v[4:5]
	v_mov_b32_e32 v64, v3
	v_pk_add_f32 v[2:3], v[64:65], v[4:5]
	s_nop 0
	s_nop 0
	s_nop 0
	s_nop 0
	s_nop 0
	s_nop 0
	s_nop 0
	s_nop 0
	s_nop 0
	s_nop 0
	s_nop 0
	s_nop 0
	s_nop 0
	s_nop 0
	s_nop 0
	s_nop 0
	s_nop 0
	s_nop 0
	s_nop 0
	s_nop 0
	s_nop 0
	s_nop 0
	s_nop 0
	s_nop 1
	v_add_f32_dpp v4, v2, v2 quad_perm:[1,0,3,2] row_mask:0xf bank_mask:0xf
	s_nop 1
	v_add_f32_dpp v4, v4, v4 quad_perm:[2,3,0,1] row_mask:0xf bank_mask:0xf
	s_nop 1
	v_add_f32_dpp v4, v4, v4 row_half_mirror row_mask:0xf bank_mask:0xf
	s_nop 1
	v_add_f32_dpp v4, v4, v4 row_mirror row_mask:0xf bank_mask:0xf
	v_add_f32_dpp v5, v3, v3 quad_perm:[1,0,3,2] row_mask:0xf bank_mask:0xf
	s_nop 1
	v_add_f32_dpp v5, v5, v5 quad_perm:[2,3,0,1] row_mask:0xf bank_mask:0xf
	s_nop 1
	v_add_f32_dpp v5, v5, v5 row_half_mirror row_mask:0xf bank_mask:0xf
	s_nop 1
	v_add_f32_dpp v5, v5, v5 row_mirror row_mask:0xf bank_mask:0xf
	s_nop 1
	v_readlane_b32 s60, v4, 0
	v_readlane_b32 s61, v4, 16
	v_readlane_b32 s62, v4, 32
	v_readlane_b32 s63, v4, 48
	s_nop 2
	v_mov_b32_e32 v2, s60
	v_add_f32_e32 v2, s61, v2
	v_add_f32_e32 v2, s62, v2
	v_add_f32_e32 v2, s63, v2
	v_readlane_b32 s60, v5, 0
	v_readlane_b32 s61, v5, 16
	v_readlane_b32 s62, v5, 32
	v_readlane_b32 s63, v5, 48
	s_nop 2
	v_mov_b32_e32 v3, s60
	v_add_f32_e32 v3, s61, v3
	v_add_f32_e32 v3, s62, v3
	v_add_f32_e32 v3, s63, v3
	s_nop 0
	v_pk_fma_f32 v[64:65], v[2:3], s[16:17], v[114:115] op_sel_hi:[1,0,0]
	s_nop 0
	v_mul_f32_e32 v2, 0x4b800000, v65
	v_cmp_gt_f32_e64 s[4:5], s71, v65
	v_cmp_gt_f32_e32 vcc, s71, v64
	s_nop 0
	v_cndmask_b32_e64 v2, v65, v2, s[4:5]
	v_rsq_f32_e32 v2, v2
	s_nop 0
	v_mul_f32_e32 v3, 0x45800000, v2
	v_cndmask_b32_e64 v2, v2, v3, s[4:5]
	v_pk_mul_f32 v[4:5], v[78:79], v[2:3] op_sel_hi:[1,0]
	v_pk_mul_f32 v[6:7], v[70:71], v[2:3] op_sel_hi:[1,0]
	v_pk_mul_f32 v[8:9], v[72:73], v[2:3] op_sel_hi:[1,0]
	v_pk_mul_f32 v[2:3], v[22:23], v[2:3] op_sel_hi:[1,0]
	s_waitcnt vmcnt(2)
	v_pk_mul_f32 v[4:5], v[30:31], v[4:5]
	v_pk_mul_f32 v[6:7], v[26:27], v[6:7]
	v_pk_mul_f32 v[8:9], v[32:33], v[8:9]
	v_pk_mul_f32 v[2:3], v[28:29], v[2:3]
	s_waitcnt vmcnt(0)
	v_pk_fma_f32 v[4:5], v[38:39], v[18:19], v[4:5]
	v_pk_fma_f32 v[6:7], v[34:35], v[20:21], v[6:7]
	v_pk_fma_f32 v[8:9], v[40:41], v[76:77], v[8:9]
	v_pk_fma_f32 v[2:3], v[36:37], v[68:69], v[2:3]
	v_pk_mul_f32 v[4:5], v[14:15], v[4:5]
	v_pk_mul_f32 v[6:7], v[16:17], v[6:7]
	v_pk_mul_f32 v[8:9], v[74:75], v[8:9]
	v_pk_mul_f32 v[10:11], v[24:25], v[2:3]
	v_cvt_pk_bf16_f32 v2, v4, v5
	v_cvt_pk_bf16_f32 v3, v8, v9
	v_cvt_pk_bf16_f32 v4, v6, v7
	v_cvt_pk_bf16_f32 v5, v10, v11
	global_store_dwordx4 v[62:63], v[2:5], off offset:2048
	global_load_dwordx4 v[2:5], v[52:53], off offset:16
	s_nop 0
	global_load_dwordx4 v[6:9], v[52:53], off
	global_load_dwordx4 v[10:13], v[54:55], off offset:16
	global_load_dwordx4 v[14:17], v[54:55], off
	v_mul_f32_e32 v18, 0x4b800000, v64
	v_cndmask_b32_e32 v18, v64, v18, vcc
	v_rsq_f32_e32 v18, v18
	s_nop 0
	v_mul_f32_e32 v19, 0x45800000, v18
	v_cndmask_b32_e32 v18, v18, v19, vcc
	v_pk_mul_f32 v[20:21], v[102:103], v[18:19] op_sel_hi:[1,0]
	v_cmp_lt_i32_e32 vcc, s14, v42
	s_or_b64 s[12:13], vcc, s[12:13]
	s_waitcnt vmcnt(2)
	v_pk_mul_f32 v[6:7], v[6:7], v[20:21]
	s_waitcnt vmcnt(0)
	v_pk_fma_f32 v[6:7], v[14:15], v[98:99], v[6:7]
	v_pk_mul_f32 v[14:15], v[86:87], v[18:19] op_sel_hi:[1,0]
	v_pk_mul_f32 v[6:7], v[100:101], v[6:7]
	v_pk_mul_f32 v[2:3], v[2:3], v[14:15]
	s_nop 0
	v_pk_fma_f32 v[2:3], v[10:11], v[88:89], v[2:3]
	s_nop 0
	v_pk_mul_f32 v[10:11], v[90:91], v[2:3]
	v_pk_mul_f32 v[2:3], v[104:105], v[18:19] op_sel_hi:[1,0]
	s_nop 0
	v_pk_mul_f32 v[2:3], v[8:9], v[2:3]
	s_nop 0
	v_pk_fma_f32 v[2:3], v[16:17], v[94:95], v[2:3]
	s_nop 0
	v_pk_mul_f32 v[8:9], v[96:97], v[2:3]
	v_pk_mul_f32 v[2:3], v[66:67], v[18:19] op_sel_hi:[1,0]
	s_nop 0
	v_pk_mul_f32 v[2:3], v[4:5], v[2:3]
	v_mul_f32_e32 v4, 0xbfb8aa3b, v83
	v_exp_f32_e32 v4, v4
	v_pk_fma_f32 v[2:3], v[12:13], v[84:85], v[2:3]
	v_add_f32_e32 v4, 1.0, v4
	v_rcp_f32_e32 v93, v4
	s_nop 0
	v_pk_mul_f32 v[4:5], v[92:93], v[82:83]
	s_nop 0
	v_pk_mul_f32 v[12:13], v[4:5], v[2:3]
	v_cvt_pk_bf16_f32 v2, v6, v7
	v_cvt_pk_bf16_f32 v3, v8, v9
	v_cvt_pk_bf16_f32 v4, v10, v11
	v_cvt_pk_bf16_f32 v5, v12, v13
	global_store_dwordx4 v[62:63], v[2:5], off offset:3072
	s_andn2_b64 exec, exec, s[12:13]
	s_cbranch_execnz .LBB0_871
